# attention: one static s_setprio 1 for waves 4-7 for the whole phase
# baseline (speedup 1.0000x reference)
.LBB0_126:
	s_cmp_gt_i32 s76, -1
	s_cbranch_scc0 .LBB0_138
	s_mul_i32 s0, s22, 0x4200
	s_add_i32 s25, s0, 0
	s_add_u32 s0, s78, 0x2b000000
	s_addc_u32 s1, s79, 0
	s_lshl_b64 s[2:3], s[76:77], 10
	v_and_b32_e32 v1, 63, v2
	s_add_u32 s2, s0, s2
	s_addc_u32 s3, s1, s3
	v_lshlrev_b32_e32 v4, 2, v1
	global_load_dword v124, v4, s[2:3]
	global_load_dword v125, v4, s[2:3] offset:256
	global_load_dword v126, v4, s[2:3] offset:512
	global_load_dword v127, v4, s[2:3] offset:768
	v_mov_b32_e32 v5, v32
	v_lshl_add_u64 v[34:35], s[0:1], 0, v[4:5]
	v_lshlrev_b32_e32 v4, 9, v0
	v_lshl_add_u64 v[6:7], s[16:17], 0, v[4:5]
	v_and_b32_e32 v10, 48, v2
	v_mov_b32_e32 v11, v32
	v_lshlrev_b32_e32 v3, 4, v2
	v_bfe_u32 v1, v2, 4, 2
	v_lshl_add_u64 v[100:101], v[6:7], 0, v[10:11]
	v_and_b32_e32 v6, 0x1f0, v3
	v_mov_b32_e32 v7, v32
	v_lshl_add_u64 v[12:13], s[78:79], 0, v[6:7]
	s_mov_b64 s[0:1], 0x2a300000
	v_lshlrev_b32_e32 v33, 2, v1
	v_lshrrev_b32_e32 v3, 2, v0
	v_lshlrev_b32_e32 v8, 3, v1
	v_lshl_add_u64 v[102:103], v[12:13], 0, s[0:1]
	v_bfe_u32 v7, v2, 5, 1
	v_add_u32_e32 v1, s25, v10
	v_or_b32_e32 v3, v33, v3
	v_mov_b32_e32 v10, s25
	s_movk_i32 s0, 0x210
	v_lshlrev_b32_e32 v2, 3, v2
	v_mov_b32_e32 v9, v32
	v_mad_u32_u24 v10, v3, s0, v10
	v_and_b32_e32 v11, 24, v2
	v_lshl_add_u64 v[2:3], s[78:79], 0, v[4:5]
	v_lshl_add_u64 v[2:3], v[2:3], 0, v[8:9]
	s_mov_b64 s[0:1], 0x2c000000
	v_lshl_add_u64 v[104:105], v[2:3], 0, s[0:1]
	v_cmp_lt_i32_e32 vcc, v186, v181
	s_lshl_b32 s0, s10, 11
	s_and_b32 s0, s0, 0x3000
	v_cndmask_b32_e32 v4, v179, v186, vcc
	v_cmp_lt_i32_e32 vcc, v187, v181
	v_add_u32_e32 v6, s25, v6
	v_mul_u32_u24_e32 v2, 0x210, v7
	v_mul_u32_u24_e32 v3, 0x210, v0
	v_lshlrev_b32_e32 v113, 2, v4
	v_cndmask_b32_e32 v4, v179, v187, vcc
	s_add_i32 s24, s24, s0
	v_readlane_b32 s0, v252, 29
	s_mov_b32 s2, 0
	v_or_b32_e32 v110, 1, v180
	v_or_b32_e32 v111, 2, v180
	v_or_b32_e32 v112, 3, v180
	v_lshlrev_b32_e32 v114, 2, v4
	v_or_b32_e32 v115, v180, v7
	v_lshl_add_u32 v116, v0, 2, s0
	v_add_u32_e32 v117, v6, v2
	v_add_u32_e32 v118, v1, v3
	v_add_u32_e32 v119, v10, v11
	s_waitcnt vmcnt(0)
	s_cmp_lt_u32 s22, 4
	s_cbranch_scc1 .Latt_noprio
	s_setprio 1
.Latt_noprio:
.LBB0_128:
	s_add_i32 s25, s2, 1
	s_mov_b64 s[0:1], -1
	s_and_b64 vcc, exec, s[36:37]
	s_cbranch_vccz .LBB0_130
	v_readlane_b32 s0, v253, 3
	s_mul_i32 s0, s25, s0
	s_add_i32 s0, s0, s10
	s_lshl_b32 s0, s0, 3
	s_add_i32 s0, s0, s22
	s_cmpk_lt_i32 s0, 0x4000
	s_cselect_b32 s38, s0, -1
	s_mov_b64 s[0:1], 0

.LBB0_138:
	s_setprio 0
	s_barrier
